# phase-2 down GEMM walks its tiles in reverse order (most recently written act rows first)
# speedup vs baseline: 1.0054x; 1.0021x over previous
;     __host__ __device__ bool next(int i, Unit& u) const {
;         const long L = (long)i * G + c; if (L >= nwg) return false;
;         int wgid = (int)L; { const int q = nwg / NXCD, r = nwg % NXCD, xcd = wgid % NXCD, off = wgid / NXCD; wgid = (xcd < r ? xcd * (q + 1) : r * (q + 1) + (xcd - r) * q) + off; }
;         const int nig = WGM * nN, gid = wgid / nig, fm = gid * WGM, gsz = (nM - fm) < WGM ? (nM - fm) : WGM;
;         u.pm = fm + ((wgid % nig) % gsz); u.pn = (wgid % nig) / gsz; return true;
; template <class Epi, class Sched, bool ALIGN_EPI = false, bool SP2 = false>
; __device__ __forceinline__ void gemm_phase(PG8_LAS unsigned char* lds, const Gemm g, const Sched& S, const Epi& E) {
;     ...
;     if (!S.next(0, cur)) return;
.LBB0_443:
	s_cmpk_lt_i32 s18, 0x200
	s_movk_i32 s0, 0xb00
	s_cselect_b64 s[2:3], -1, 0
	s_cmpk_gt_i32 s18, 0x1ff
	v_readfirstlane_b32 s26, v254
	s_cbranch_scc1 .LBB0_449
	s_sub_i32 s99, 0x1ff, s18
	s_ashr_i32 s1, s99, 31
	s_lshr_b32 s1, s1, 29
	s_add_i32 s1, s99, s1
	s_and_b32 s4, s1, -8
	s_sub_i32 s6, s99, s4
	s_cmp_gt_i32 s6, -1
	s_cbranch_scc0 .LBB0_446
	s_lshl_b32 s7, s6, 6
	s_cbranch_execz .LBB0_447
	s_branch .LBB0_448

;     __host__ __device__ bool next(int i, Unit& u) const {
;         const long L = (long)i * G + c; if (L >= nwg) return false;
;         int wgid = (int)L; { const int q = nwg / NXCD, r = nwg % NXCD, xcd = wgid % NXCD, off = wgid / NXCD; wgid = (xcd < r ? xcd * (q + 1) : r * (q + 1) + (xcd - r) * q) + off; }
;         const int nig = WGM * nN, gid = wgid / nig, fm = gid * WGM, gsz = (nM - fm) < WGM ? (nM - fm) : WGM;
;         u.pm = fm + ((wgid % nig) % gsz); u.pn = (wgid % nig) / gsz; return true;
; template <class Epi, class Sched, bool ALIGN_EPI = false, bool SP2 = false>
; __device__ __forceinline__ void gemm_phase(PG8_LAS unsigned char* lds, const Gemm g, const Sched& S, const Epi& E) {
;     ...
;         const bool has_next = S.next(ui + 1, nxt);
;         const char* nA = has_next ? (const char*)g.A + (size_t)nxt.pm * tstep : cA; const char* nB = has_next ? (const char*)g.Bt + (size_t)nxt.pn * tstep : cB;
.LBB0_455:
	v_lshl_add_u32 v252, s64, 8, v156
	v_lshl_or_b32 v253, s14, 8, v158
	v_lshlrev_b32_e32 v253, 1, v253
	v_lshl_add_u32 v252, v252, 11, v253
	global_load_dwordx4 v[230:233], v252, s[42:43]
	global_load_dwordx4 v[234:237], v252, s[42:43] offset:256
	v_add_u32_e32 v253, 0x8000, v252
	global_load_dwordx4 v[238:241], v253, s[42:43]
	global_load_dwordx4 v[242:245], v253, s[42:43] offset:256
	v_add_u32_e32 v253, 0x10000, v252
	global_load_dwordx4 v[246:249], v253, s[42:43]
	global_load_dwordx4 v[250:253], v253, s[42:43] offset:256
	s_add_i32 s61, s61, 1
	s_mul_i32 s0, s61, s50
	s_mul_hi_u32 s1, s61, s51
	s_add_i32 s1, s1, s0
	s_mul_i32 s0, s61, s51
	s_add_u32 s4, s0, s18
	s_addc_u32 s5, s1, s58
	v_cmp_gt_i64_e32 vcc, s[4:5], v[142:143]
	v_cmp_lt_i64_e64 s[0:1], s[4:5], v[140:141]
	s_cbranch_vccnz .LBB0_461
	s_sub_i32 s4, 0x1ff, s4
	s_ashr_i32 s5, s4, 31
	s_lshr_b32 s5, s5, 29
	s_add_i32 s28, s4, s5
	s_and_b32 s5, s28, -8
	s_sub_i32 s29, s4, s5
	s_cmp_gt_i32 s29, -1
	s_mov_b64 s[4:5], -1
	s_cbranch_scc0 .LBB0_458
	s_lshl_b32 s62, s29, 6
	s_mov_b64 s[4:5], 0

; __global__ void __launch_bounds__(512, 2) fwd_megakernel(Params P) {
;     extern __shared__ __attribute__((aligned(16))) unsigned char lds_raw[];
	.amdhsa_kernel _Z14fwd_megakernel6Params
		.amdhsa_group_segment_fixed_size 0
		.amdhsa_private_segment_fixed_size 0
		.amdhsa_kernarg_size 528
		.amdhsa_user_sgpr_count 2
		.amdhsa_user_sgpr_dispatch_ptr 0
		.amdhsa_user_sgpr_queue_ptr 0
		.amdhsa_user_sgpr_kernarg_segment_ptr 1
		.amdhsa_user_sgpr_dispatch_id 0
		.amdhsa_user_sgpr_kernarg_preload_length 0
		.amdhsa_user_sgpr_kernarg_preload_offset 0
		.amdhsa_user_sgpr_private_segment_size 0
		.amdhsa_uses_dynamic_stack 0
		.amdhsa_enable_private_segment 0
		.amdhsa_system_sgpr_workgroup_id_x 1
		.amdhsa_system_sgpr_workgroup_id_y 0
		.amdhsa_system_sgpr_workgroup_id_z 0
		.amdhsa_system_sgpr_workgroup_info 0
		.amdhsa_system_vgpr_workitem_id 2
		.amdhsa_next_free_vgpr 256
		.amdhsa_next_free_sgpr 102
		.amdhsa_accum_offset 256
		.amdhsa_reserve_vcc 1
		.amdhsa_float_round_mode_32 0
		.amdhsa_float_round_mode_16_64 0
		.amdhsa_float_denorm_mode_32 3
		.amdhsa_float_denorm_mode_16_64 3
		.amdhsa_dx10_clamp 1
		.amdhsa_ieee_mode 1
		.amdhsa_fp16_overflow 0
		.amdhsa_tg_split 0
		.amdhsa_exception_fp_ieee_invalid_op 0
		.amdhsa_exception_fp_denorm_src 0
		.amdhsa_exception_fp_ieee_div_zero 0
		.amdhsa_exception_fp_ieee_overflow 0
		.amdhsa_exception_fp_ieee_underflow 0
		.amdhsa_exception_fp_ieee_inexact 0
		.amdhsa_exception_int_div_zero 0
	.end_amdhsa_kernel

; __global__ void __launch_bounds__(512, 2) fwd_megakernel(Params P) {
;     extern __shared__ __attribute__((aligned(16))) unsigned char lds_raw[];
amdhsa.kernels:
  - .agpr_count:     0
    .args:
      - .offset:         0
        .size:           272
        .value_kind:     by_value
      - .offset:         272
        .size:           4
        .value_kind:     hidden_block_count_x
      - .offset:         276
        .size:           4
        .value_kind:     hidden_block_count_y
      - .offset:         280
        .size:           4
        .value_kind:     hidden_block_count_z
      - .offset:         284
        .size:           2
        .value_kind:     hidden_group_size_x
      - .offset:         286
        .size:           2
        .value_kind:     hidden_group_size_y
      - .offset:         288
        .size:           2
        .value_kind:     hidden_group_size_z
      - .offset:         290
        .size:           2
        .value_kind:     hidden_remainder_x
      - .offset:         292
        .size:           2
        .value_kind:     hidden_remainder_y
      - .offset:         294
        .size:           2
        .value_kind:     hidden_remainder_z
      - .offset:         312
        .size:           8
        .value_kind:     hidden_global_offset_x
      - .offset:         320
        .size:           8
        .value_kind:     hidden_global_offset_y
      - .offset:         328
        .size:           8
        .value_kind:     hidden_global_offset_z
      - .offset:         336
        .size:           2
        .value_kind:     hidden_grid_dims
      - .offset:         360
        .size:           8
        .value_kind:     hidden_multigrid_sync_arg
      - .offset:         392
        .size:           4
        .value_kind:     hidden_dynamic_lds_size
    .group_segment_fixed_size: 0
    .kernarg_segment_align: 8
    .kernarg_segment_size: 528
    .language:       OpenCL C
    .language_version:
      - 2
      - 0
    .max_flat_workgroup_size: 512
    .name:           _Z14fwd_megakernel6Params
    .private_segment_fixed_size: 0
    .sgpr_count:     108
    .sgpr_spill_count: 42
    .symbol:         _Z14fwd_megakernel6Params.kd
    .uniform_work_group_size: 1
    .uses_dynamic_stack: false
    .vgpr_count:     256
    .vgpr_spill_count: 0
    .wavefront_size: 64
